# v054 + no vmcnt(0) store drain between F3a->F3b and F9a->F9b (no seam follows; the next K-loop's in-order counted waits cover them)
# baseline (speedup 1.0000x reference)
.LBB0_670:
	v_readlane_b32 s72, v254, 4
	v_readlane_b32 s73, v254, 5
	v_readlane_b32 s31, v255, 9
	v_readlane_b32 s77, v255, 27
	s_barrier

.LBB0_1580:
	v_readlane_b32 s72, v254, 4
	v_readlane_b32 s85, v255, 4
	v_readlane_b32 s73, v254, 5
	v_readlane_b32 s31, v255, 9
	s_barrier
